# projection epilogue fast path for the PB column units: v_permlane16_swap pairs and 16 x 16-byte stores per lane instead of 32 x 8-byte through per-store branches
# speedup vs baseline: 1.0113x; 1.0035x over previous
; #define PG8_STAGE(bufoff, gbase, voff) do { _Pragma("unroll") for (int _i = 0; _i < 2; ++_i) \
;     __builtin_amdgcn_global_load_lds((const unsigned*)((const char*)(gbase) + (voff)[_i]), (PG8_LAS unsigned*)(lds + (bufoff) + ldsw + _i * 8192), 16, 0, 0); } while (0)
; #define PG8_LDA(dst, b, h) do { _Pragma("unroll") for (int m = 0; m < 4; ++m) _Pragma("unroll") for (int k = 0; k < 2; ++k) dst[m][k] = *(const PG8_LAS bf16x8*)(lds + PG8_SA(b, h) + aoff + m * 2048 + k * 1024); } while (0)
; #define PG8_LDB(dst, b, h) do { _Pragma("unroll") for (int n = 0; n < 2; ++n) _Pragma("unroll") for (int k = 0; k < 2; ++k) dst[n][k] = *(const PG8_LAS bf16x8*)(lds + PG8_SB(b, h) + boff + n * 2048 + k * 1024); } while (0)
; #define PG8_MMA(ai, bj, At, Bt) do { __builtin_amdgcn_s_setprio(1); _Pragma("unroll") for (int m = 0; m < 4; ++m) _Pragma("unroll") for (int n = 0; n < 2; ++n) _Pragma("unroll") for (int k = 0; k < 2; ++k) \
;     acc[ai][bj][m][n] = __builtin_amdgcn_mfma_f32_16x16x32_bf16(Bt[n][k], At[m][k], acc[ai][bj][m][n], 0, 0, 0); __builtin_amdgcn_s_setprio(0); } while (0)
; #define PG8_WAIT_V(n) asm volatile("s_waitcnt vmcnt(" #n ")" ::: "memory")
; #define PG8_WAIT_L(n) asm volatile("s_waitcnt lgkmcnt(" #n ")" ::: "memory")
; #define PG8_BAR __builtin_amdgcn_s_barrier()
; #define PG8_SCHED __builtin_amdgcn_sched_barrier(0)
; template <class Epi, class Sched>
; __device__ __forceinline__ void gemm_phase(PG8_LAS unsigned char* lds, const int lda, const int ldb, const Sched& S, const Epi& E) {
;     ...
;       PG8_LDB(B0, 0, 0); PG8_SCHED; PG8_LDA(At, 0, 0); PG8_STAGE(PG8_SA(1, 1), a1 + hstepA, voffA);
;       PG8_WAIT_L(8); PG8_BAR; PG8_WAIT_L(0); PG8_MMA(0, 0, At, B0); PG8_BAR; PG8_SCHED;
;       PG8_LDB(B1, 0, 1); PG8_STAGE(PG8_SB(0, 0), b2, voffB);
;       PG8_BAR; PG8_WAIT_L(0); PG8_MMA(0, 1, At, B1); PG8_BAR;
;       PG8_LDA(At, 0, 1); PG8_STAGE(PG8_SA(0, 0), a2, voffA);
;       PG8_BAR; PG8_WAIT_L(0); PG8_MMA(1, 0, At, B0); PG8_BAR; PG8_SCHED;
;       PG8_STAGE(PG8_SB(0, 1), b2 + hstepB, voffB);
;       PG8_WAIT_V(6); PG8_BAR; PG8_MMA(1, 1, At, B1); PG8_BAR;
.LBB0_335:
	s_add_u32 s10, s8, 0xfffc0080
	s_addc_u32 s11, s9, -1
	s_add_i32 s31, 0, 0x10000
	v_add_u32_e32 v156, s31, v131
	ds_read_b128 v[144:147], v156
	ds_read_b128 v[148:151], v156 offset:1024
	ds_read_b128 v[152:155], v156 offset:2048
	ds_read_b128 v[200:203], v156 offset:3072
	s_cmp_eq_u32 s30, 12
	s_cselect_b32 s25, s17, s11
	s_cselect_b32 s24, s26, s10
	s_cselect_b32 s11, s15, s29
	s_cselect_b32 s10, s27, s28
	v_lshl_add_u64 v[156:157], s[8:9], 0, v[140:141]
	s_add_i32 m0, s40, 0xc000
	ds_read_b128 v[204:207], v172
	ds_read_b128 v[208:211], v172 offset:1024
	ds_read_b128 v[212:215], v172 offset:2048
	ds_read_b128 v[216:219], v172 offset:3072
	ds_read_b128 v[220:223], v172 offset:4096
	ds_read_b128 v[224:227], v172 offset:5120
	ds_read_b128 v[228:231], v172 offset:6144
	ds_read_b128 v[232:235], v172 offset:7168
	global_load_lds_dwordx4 v[156:157], off
	v_lshl_add_u64 v[156:157], s[8:9], 0, v[142:143]
	s_add_i32 m0, s40, 0xe000
	s_nop 0
	global_load_lds_dwordx4 v[156:157], off
	s_waitcnt lgkmcnt(8)
	s_barrier
	s_waitcnt lgkmcnt(0)
	v_mfma_f32_16x16x32_bf16 v[126:129], v[144:147], v[204:207], v[126:129]
	v_mfma_f32_16x16x32_bf16 v[122:125], v[152:155], v[204:207], v[122:125]
	v_mfma_f32_16x16x32_bf16 v[110:113], v[144:147], v[212:215], v[110:113]
	v_mfma_f32_16x16x32_bf16 v[106:109], v[152:155], v[212:215], v[106:109]
	v_mfma_f32_16x16x32_bf16 v[94:97], v[144:147], v[220:223], v[94:97]
	v_mfma_f32_16x16x32_bf16 v[90:93], v[152:155], v[220:223], v[90:93]
	v_mfma_f32_16x16x32_bf16 v[78:81], v[144:147], v[228:231], v[78:81]
	v_mfma_f32_16x16x32_bf16 v[74:77], v[152:155], v[228:231], v[74:77]
	v_mfma_f32_16x16x32_bf16 v[126:129], v[148:151], v[208:211], v[126:129]
	v_mfma_f32_16x16x32_bf16 v[122:125], v[200:203], v[208:211], v[122:125]
	v_mfma_f32_16x16x32_bf16 v[110:113], v[148:151], v[216:219], v[110:113]
	v_mfma_f32_16x16x32_bf16 v[106:109], v[200:203], v[216:219], v[106:109]
	v_mfma_f32_16x16x32_bf16 v[94:97], v[148:151], v[224:227], v[94:97]
	v_mfma_f32_16x16x32_bf16 v[90:93], v[200:203], v[224:227], v[90:93]
	v_mfma_f32_16x16x32_bf16 v[78:81], v[148:151], v[232:235], v[78:81]
	v_mfma_f32_16x16x32_bf16 v[74:77], v[200:203], v[232:235], v[74:77]
	s_barrier
	s_add_i32 s33, 0, 0x14000
	v_add_u32_e32 v156, s33, v131
	s_add_i32 s31, s31, s39
	ds_read_b128 v[236:239], v156
	ds_read_b128 v[240:243], v156 offset:1024
	ds_read_b128 v[244:247], v156 offset:2048
	ds_read_b128 v[248:251], v156 offset:3072
	v_lshl_add_u64 v[156:157], s[10:11], 0, v[134:135]
	s_mov_b32 m0, s31
	v_lshl_add_u64 v[174:175], s[10:11], 0, v[132:133]
	global_load_lds_dwordx4 v[156:157], off
	s_add_i32 m0, s31, 0x2000
	s_nop 0
	global_load_lds_dwordx4 v[174:175], off
	s_barrier
	s_waitcnt lgkmcnt(0)
	v_mfma_f32_16x16x32_bf16 v[118:121], v[236:239], v[204:207], v[118:121]
	v_mfma_f32_16x16x32_bf16 v[114:117], v[244:247], v[204:207], v[114:117]
	v_mfma_f32_16x16x32_bf16 v[102:105], v[236:239], v[212:215], v[102:105]
	v_mfma_f32_16x16x32_bf16 v[98:101], v[244:247], v[212:215], v[98:101]
	v_mfma_f32_16x16x32_bf16 v[86:89], v[236:239], v[220:223], v[86:89]
	v_mfma_f32_16x16x32_bf16 v[82:85], v[244:247], v[220:223], v[82:85]
	v_mfma_f32_16x16x32_bf16 v[70:73], v[236:239], v[228:231], v[70:73]
	v_mfma_f32_16x16x32_bf16 v[66:69], v[244:247], v[228:231], v[66:69]
	v_mfma_f32_16x16x32_bf16 v[118:121], v[240:243], v[208:211], v[118:121]
	v_mfma_f32_16x16x32_bf16 v[114:117], v[248:251], v[208:211], v[114:117]
	v_mfma_f32_16x16x32_bf16 v[102:105], v[240:243], v[216:219], v[102:105]
	v_mfma_f32_16x16x32_bf16 v[98:101], v[248:251], v[216:219], v[98:101]
	v_mfma_f32_16x16x32_bf16 v[86:89], v[240:243], v[224:227], v[86:89]
	v_mfma_f32_16x16x32_bf16 v[82:85], v[248:251], v[224:227], v[82:85]
	v_mfma_f32_16x16x32_bf16 v[70:73], v[240:243], v[232:235], v[70:73]
	v_mfma_f32_16x16x32_bf16 v[66:69], v[248:251], v[232:235], v[66:69]
	s_barrier
	s_mov_b32 m0, s40
	v_lshl_add_u64 v[182:183], s[24:25], 0, v[134:135]
	ds_read_b128 v[204:207], v172 offset:16384
	ds_read_b128 v[208:211], v172 offset:17408
	ds_read_b128 v[212:215], v172 offset:18432
	ds_read_b128 v[216:219], v172 offset:19456
	ds_read_b128 v[220:223], v172 offset:20480
	ds_read_b128 v[224:227], v172 offset:21504
	ds_read_b128 v[228:231], v172 offset:22528
	ds_read_b128 v[232:235], v172 offset:23552
	global_load_lds_dwordx4 v[182:183], off
	v_lshl_add_u64 v[184:185], s[24:25], 0, v[132:133]
	s_mov_b32 m0, s41
	s_nop 0
	global_load_lds_dwordx4 v[184:185], off
	s_barrier
	s_waitcnt lgkmcnt(0)
	v_mfma_f32_16x16x32_bf16 v[62:65], v[144:147], v[204:207], v[62:65]
	v_mfma_f32_16x16x32_bf16 v[58:61], v[152:155], v[204:207], v[58:61]
	v_mfma_f32_16x16x32_bf16 v[46:49], v[144:147], v[212:215], v[46:49]
	v_mfma_f32_16x16x32_bf16 v[42:45], v[152:155], v[212:215], v[42:45]
	v_mfma_f32_16x16x32_bf16 v[30:33], v[144:147], v[220:223], v[30:33]
	v_mfma_f32_16x16x32_bf16 v[26:29], v[152:155], v[220:223], v[26:29]
	v_mfma_f32_16x16x32_bf16 v[14:17], v[144:147], v[228:231], v[14:17]
	v_mfma_f32_16x16x32_bf16 v[10:13], v[152:155], v[228:231], v[10:13]
	v_mfma_f32_16x16x32_bf16 v[62:65], v[148:151], v[208:211], v[62:65]
	v_mfma_f32_16x16x32_bf16 v[58:61], v[200:203], v[208:211], v[58:61]
	v_mfma_f32_16x16x32_bf16 v[46:49], v[148:151], v[216:219], v[46:49]
	v_mfma_f32_16x16x32_bf16 v[42:45], v[200:203], v[216:219], v[42:45]
	v_mfma_f32_16x16x32_bf16 v[30:33], v[148:151], v[224:227], v[30:33]
	v_mfma_f32_16x16x32_bf16 v[26:29], v[200:203], v[224:227], v[26:29]
	v_mfma_f32_16x16x32_bf16 v[14:17], v[148:151], v[232:235], v[14:17]
	v_mfma_f32_16x16x32_bf16 v[10:13], v[200:203], v[232:235], v[10:13]
	s_barrier
; #define PG8_STAGE(bufoff, gbase, voff) do { _Pragma("unroll") for (int _i = 0; _i < 2; ++_i) \
;     __builtin_amdgcn_global_load_lds((const unsigned*)((const char*)(gbase) + (voff)[_i]), (PG8_LAS unsigned*)(lds + (bufoff) + ldsw + _i * 8192), 16, 0, 0); } while (0)
; #define PG8_LDA(dst, b, h) do { _Pragma("unroll") for (int m = 0; m < 4; ++m) _Pragma("unroll") for (int k = 0; k < 2; ++k) dst[m][k] = *(const PG8_LAS bf16x8*)(lds + PG8_SA(b, h) + aoff + m * 2048 + k * 1024); } while (0)
; #define PG8_LDB(dst, b, h) do { _Pragma("unroll") for (int n = 0; n < 2; ++n) _Pragma("unroll") for (int k = 0; k < 2; ++k) dst[n][k] = *(const PG8_LAS bf16x8*)(lds + PG8_SB(b, h) + boff + n * 2048 + k * 1024); } while (0)
; #define PG8_MMA(ai, bj, At, Bt) do { __builtin_amdgcn_s_setprio(1); _Pragma("unroll") for (int m = 0; m < 4; ++m) _Pragma("unroll") for (int n = 0; n < 2; ++n) _Pragma("unroll") for (int k = 0; k < 2; ++k) \
;     acc[ai][bj][m][n] = __builtin_amdgcn_mfma_f32_16x16x32_bf16(Bt[n][k], At[m][k], acc[ai][bj][m][n], 0, 0, 0); __builtin_amdgcn_s_setprio(0); } while (0)
; #define PG8_WAIT_V(n) asm volatile("s_waitcnt vmcnt(" #n ")" ::: "memory")
; #define PG8_WAIT_L(n) asm volatile("s_waitcnt lgkmcnt(" #n ")" ::: "memory")
; #define PG8_BAR __builtin_amdgcn_s_barrier()
; #define PG8_SCHED __builtin_amdgcn_sched_barrier(0)
; template <class Epi, class Sched>
; __device__ __forceinline__ void gemm_phase(PG8_LAS unsigned char* lds, const int lda, const int ldb, const Sched& S, const Epi& E) {
;     ...
;       PG8_STAGE(PG8_SB(0, 1), b2 + hstepB, voffB);
;       PG8_WAIT_V(6); PG8_BAR; PG8_MMA(1, 1, At, B1); PG8_BAR;
;       PG8_LDB(B0, 1, 0); PG8_SCHED; PG8_LDA(At, 1, 0); PG8_STAGE(PG8_SA(0, 1), a2 + hstepA, voffA);
;       PG8_WAIT_L(8); PG8_BAR; PG8_WAIT_L(0); PG8_MMA(0, 0, At, B0); PG8_BAR; PG8_SCHED;
;       PG8_LDB(B1, 1, 1); PG8_STAGE(PG8_SB(1, 0), b3, voffB);
;       PG8_BAR; PG8_WAIT_L(0); PG8_MMA(0, 1, At, B1); PG8_BAR;
;       PG8_LDA(At, 1, 1); PG8_STAGE(PG8_SA(1, 0), a3, voffA);
;       PG8_BAR; PG8_WAIT_L(0); PG8_MMA(1, 0, At, B0); PG8_BAR; PG8_SCHED;
	s_add_u32 s34, s10, 0x40000
	s_addc_u32 s35, s11, 0
	s_add_i32 s31, s33, s39
	v_lshl_add_u64 v[144:145], s[34:35], 0, v[134:135]
	s_mov_b32 m0, s31
	s_nop 0
	global_load_lds_dwordx4 v[144:145], off
	v_lshl_add_u64 v[144:145], s[34:35], 0, v[132:133]
	s_add_i32 m0, s31, 0x2000
	s_nop 0
	global_load_lds_dwordx4 v[144:145], off
	s_waitcnt vmcnt(6)
	s_barrier
	v_mfma_f32_16x16x32_bf16 v[54:57], v[236:239], v[204:207], v[54:57]
	v_mfma_f32_16x16x32_bf16 v[50:53], v[244:247], v[204:207], v[50:53]
	v_mfma_f32_16x16x32_bf16 v[38:41], v[236:239], v[212:215], v[38:41]
	v_mfma_f32_16x16x32_bf16 v[34:37], v[244:247], v[212:215], v[34:37]
	v_mfma_f32_16x16x32_bf16 v[22:25], v[236:239], v[220:223], v[22:25]
	v_mfma_f32_16x16x32_bf16 v[18:21], v[244:247], v[220:223], v[18:21]
	v_mfma_f32_16x16x32_bf16 v[6:9], v[236:239], v[228:231], v[6:9]
	v_mfma_f32_16x16x32_bf16 v[2:5], v[244:247], v[228:231], v[2:5]
	v_mfma_f32_16x16x32_bf16 v[54:57], v[240:243], v[208:211], v[54:57]
	v_mfma_f32_16x16x32_bf16 v[50:53], v[248:251], v[208:211], v[50:53]
	v_mfma_f32_16x16x32_bf16 v[38:41], v[240:243], v[216:219], v[38:41]
	v_mfma_f32_16x16x32_bf16 v[34:37], v[248:251], v[216:219], v[34:37]
	v_mfma_f32_16x16x32_bf16 v[22:25], v[240:243], v[224:227], v[22:25]
	v_mfma_f32_16x16x32_bf16 v[18:21], v[248:251], v[224:227], v[18:21]
	v_mfma_f32_16x16x32_bf16 v[6:9], v[240:243], v[232:235], v[6:9]
	v_mfma_f32_16x16x32_bf16 v[2:5], v[248:251], v[232:235], v[2:5]
	s_barrier
	s_add_i32 s31, 0, 0x18000
	v_add_u32_e32 v173, s31, v131
	ds_read_b128 v[144:147], v173
	ds_read_b128 v[148:151], v173 offset:1024
	ds_read_b128 v[152:155], v173 offset:2048
	ds_read_b128 v[200:203], v173 offset:3072
	s_add_u32 s24, s24, 0x40000
	s_addc_u32 s25, s25, 0
	s_mov_b32 m0, s42
	v_lshl_add_u64 v[236:237], s[24:25], 0, v[134:135]
	ds_read_b128 v[204:207], v172 offset:32768
	ds_read_b128 v[208:211], v172 offset:33792
	ds_read_b128 v[212:215], v172 offset:34816
	ds_read_b128 v[216:219], v172 offset:35840
	ds_read_b128 v[220:223], v172 offset:36864
	ds_read_b128 v[224:227], v172 offset:37888
	ds_read_b128 v[228:231], v172 offset:38912
	ds_read_b128 v[232:235], v172 offset:39936
	global_load_lds_dwordx4 v[236:237], off
	v_lshl_add_u64 v[236:237], s[24:25], 0, v[132:133]
	s_mov_b32 m0, s43
	s_nop 0
	global_load_lds_dwordx4 v[236:237], off
	s_waitcnt lgkmcnt(8)
	s_barrier
	s_waitcnt lgkmcnt(0)
	v_mfma_f32_16x16x32_bf16 v[126:129], v[144:147], v[204:207], v[126:129]
	v_mfma_f32_16x16x32_bf16 v[122:125], v[152:155], v[204:207], v[122:125]
	v_mfma_f32_16x16x32_bf16 v[110:113], v[144:147], v[212:215], v[110:113]
	v_mfma_f32_16x16x32_bf16 v[106:109], v[152:155], v[212:215], v[106:109]
	v_mfma_f32_16x16x32_bf16 v[94:97], v[144:147], v[220:223], v[94:97]
	v_mfma_f32_16x16x32_bf16 v[90:93], v[152:155], v[220:223], v[90:93]
	v_mfma_f32_16x16x32_bf16 v[78:81], v[144:147], v[228:231], v[78:81]
	v_mfma_f32_16x16x32_bf16 v[74:77], v[152:155], v[228:231], v[74:77]
	v_mfma_f32_16x16x32_bf16 v[126:129], v[148:151], v[208:211], v[126:129]
	v_mfma_f32_16x16x32_bf16 v[122:125], v[200:203], v[208:211], v[122:125]
	v_mfma_f32_16x16x32_bf16 v[110:113], v[148:151], v[216:219], v[110:113]
	v_mfma_f32_16x16x32_bf16 v[106:109], v[200:203], v[216:219], v[106:109]
	v_mfma_f32_16x16x32_bf16 v[94:97], v[148:151], v[224:227], v[94:97]
	v_mfma_f32_16x16x32_bf16 v[90:93], v[200:203], v[224:227], v[90:93]
	v_mfma_f32_16x16x32_bf16 v[78:81], v[148:151], v[232:235], v[78:81]
	v_mfma_f32_16x16x32_bf16 v[74:77], v[200:203], v[232:235], v[74:77]
	s_barrier
	s_add_i32 s24, 0, 0x1c000
	s_add_i32 s25, s31, s39
	v_add_u32_e32 v173, s24, v131
	v_lshl_add_u64 v[156:157], v[156:157], 0, s[86:87]
	s_mov_b32 m0, s25
	ds_read_b128 v[236:239], v173
	ds_read_b128 v[240:243], v173 offset:1024
	ds_read_b128 v[244:247], v173 offset:2048
	ds_read_b128 v[248:251], v173 offset:3072
	global_load_lds_dwordx4 v[156:157], off
	v_lshl_add_u64 v[156:157], v[174:175], 0, s[86:87]
	s_add_i32 m0, s25, 0x2000
	s_nop 0
	global_load_lds_dwordx4 v[156:157], off
	s_barrier
	s_waitcnt lgkmcnt(0)
	v_mfma_f32_16x16x32_bf16 v[118:121], v[236:239], v[204:207], v[118:121]
	v_mfma_f32_16x16x32_bf16 v[114:117], v[244:247], v[204:207], v[114:117]
	v_mfma_f32_16x16x32_bf16 v[102:105], v[236:239], v[212:215], v[102:105]
	v_mfma_f32_16x16x32_bf16 v[98:101], v[244:247], v[212:215], v[98:101]
	v_mfma_f32_16x16x32_bf16 v[86:89], v[236:239], v[220:223], v[86:89]
	v_mfma_f32_16x16x32_bf16 v[82:85], v[244:247], v[220:223], v[82:85]
	v_mfma_f32_16x16x32_bf16 v[70:73], v[236:239], v[228:231], v[70:73]
	v_mfma_f32_16x16x32_bf16 v[66:69], v[244:247], v[228:231], v[66:69]
	v_mfma_f32_16x16x32_bf16 v[118:121], v[240:243], v[208:211], v[118:121]
	v_mfma_f32_16x16x32_bf16 v[114:117], v[248:251], v[208:211], v[114:117]
	v_mfma_f32_16x16x32_bf16 v[102:105], v[240:243], v[216:219], v[102:105]
	v_mfma_f32_16x16x32_bf16 v[98:101], v[248:251], v[216:219], v[98:101]
	v_mfma_f32_16x16x32_bf16 v[86:89], v[240:243], v[224:227], v[86:89]
	v_mfma_f32_16x16x32_bf16 v[82:85], v[248:251], v[224:227], v[82:85]
	v_mfma_f32_16x16x32_bf16 v[70:73], v[240:243], v[232:235], v[70:73]
	v_mfma_f32_16x16x32_bf16 v[66:69], v[248:251], v[232:235], v[66:69]
	s_barrier
	s_mov_b32 m0, s45
	v_lshl_add_u64 v[156:157], v[182:183], 0, s[86:87]
	ds_read_b128 v[204:207], v172 offset:49152
	ds_read_b128 v[208:211], v172 offset:50176
	ds_read_b128 v[212:215], v172 offset:51200
	ds_read_b128 v[216:219], v172 offset:52224
	ds_read_b128 v[220:223], v172 offset:53248
	ds_read_b128 v[224:227], v172 offset:54272
	ds_read_b128 v[228:231], v172 offset:55296
	ds_read_b128 v[232:235], v172 offset:56320
	global_load_lds_dwordx4 v[156:157], off
	v_lshl_add_u64 v[156:157], v[184:185], 0, s[86:87]
	s_mov_b32 m0, s46
	s_nop 0
	global_load_lds_dwordx4 v[156:157], off
	s_barrier
; #define PG8_STAGE(bufoff, gbase, voff) do { _Pragma("unroll") for (int _i = 0; _i < 2; ++_i) \
;     __builtin_amdgcn_global_load_lds((const unsigned*)((const char*)(gbase) + (voff)[_i]), (PG8_LAS unsigned*)(lds + (bufoff) + ldsw + _i * 8192), 16, 0, 0); } while (0)
; #define PG8_MMA(ai, bj, At, Bt) do { __builtin_amdgcn_s_setprio(1); _Pragma("unroll") for (int m = 0; m < 4; ++m) _Pragma("unroll") for (int n = 0; n < 2; ++n) _Pragma("unroll") for (int k = 0; k < 2; ++k) \
;     acc[ai][bj][m][n] = __builtin_amdgcn_mfma_f32_16x16x32_bf16(Bt[n][k], At[m][k], acc[ai][bj][m][n], 0, 0, 0); __builtin_amdgcn_s_setprio(0); } while (0)
; template <class Epi, class Sched>
; __device__ __forceinline__ void gemm_phase(PG8_LAS unsigned char* lds, const int lda, const int ldb, const Sched& S, const Epi& E) {
;     ...
;       PG8_BAR; PG8_WAIT_L(0); PG8_MMA(1, 0, At, B0); PG8_BAR; PG8_SCHED;
;       PG8_STAGE(PG8_SB(1, 1), b3 + hstepB, voffB);
;       PG8_WAIT_V(6); PG8_BAR; PG8_MMA(1, 1, At, B1); PG8_BAR;
;   __device__ __forceinline__ void operator()(const f32x4 (&acc)[2][2][4][2], const Unit& u, int wr, int wc, int fr, int fq) const {
; #pragma unroll
;     for (int ai = 0; ai < 2; ++ai)
; #pragma unroll
;       for (int m = 0; m < 4; ++m) {
;         const int r = u.pm * 256 + ai * 128 + wr * 64 + m * 16 + fr;
; #pragma unroll
;         for (int bj = 0; bj < 2; ++bj)
; #pragma unroll
;           for (int n = 0; n < 2; ++n) {
;             const f32x4 v = acc[ai][bj][m][n];
;             const int c = u.pn * 256 + bj * 128 + wc * 32 + n * 16 + 4 * fq;
;             if (u.pn < 7) {
;               uint2 w; w.x = pack2(v[0], v[1]); w.y = pack2(v[2], v[3]);
;               *reinterpret_cast<uint2*>(PB + (size_t)r * PBW + c) = w;
;             } else {
;               const int nn = c - 1792, part = nn >> 8, ch = nn & 255;
;               if (u.pn == 7 && bj == 0 && wc == 1 && n == 1) {
;                 *reinterpret_cast<float4*>(AB + (size_t)r * 16 + 4 * fq) = make_float4(v[0], v[1], v[2], v[3]);
;               } else {
;                 u16* d; int cstride;
;                 if (r < ML) { const int b = r >> 11, tt = r & 2047; d = FT + ((size_t)(b * 256)) * 4096 + part * 2048 + tt; cstride = 4096; }
;                 else { const int rc = r - ML, b = rc >> 8, tt = rc & 255; d = FTC + ((size_t)(b * 256)) * 512 + part * 256 + tt; cstride = 512; }
	s_waitcnt lgkmcnt(0)
	v_mfma_f32_16x16x32_bf16 v[62:65], v[144:147], v[204:207], v[62:65]
	v_mfma_f32_16x16x32_bf16 v[58:61], v[152:155], v[204:207], v[58:61]
	v_mfma_f32_16x16x32_bf16 v[46:49], v[144:147], v[212:215], v[46:49]
	v_mfma_f32_16x16x32_bf16 v[42:45], v[152:155], v[212:215], v[42:45]
	v_mfma_f32_16x16x32_bf16 v[30:33], v[144:147], v[220:223], v[30:33]
	v_mfma_f32_16x16x32_bf16 v[26:29], v[152:155], v[220:223], v[26:29]
	v_mfma_f32_16x16x32_bf16 v[14:17], v[144:147], v[228:231], v[14:17]
	v_mfma_f32_16x16x32_bf16 v[10:13], v[152:155], v[228:231], v[10:13]
	v_mfma_f32_16x16x32_bf16 v[62:65], v[148:151], v[208:211], v[62:65]
	v_mfma_f32_16x16x32_bf16 v[58:61], v[200:203], v[208:211], v[58:61]
	v_mfma_f32_16x16x32_bf16 v[46:49], v[148:151], v[216:219], v[46:49]
	v_mfma_f32_16x16x32_bf16 v[42:45], v[200:203], v[216:219], v[42:45]
	v_mfma_f32_16x16x32_bf16 v[30:33], v[148:151], v[224:227], v[30:33]
	v_mfma_f32_16x16x32_bf16 v[26:29], v[200:203], v[224:227], v[26:29]
	v_mfma_f32_16x16x32_bf16 v[14:17], v[148:151], v[232:235], v[14:17]
	v_mfma_f32_16x16x32_bf16 v[10:13], v[200:203], v[232:235], v[10:13]
	s_barrier
	s_add_u32 s10, s10, 0x40080
	s_addc_u32 s11, s11, 0
	s_add_i32 s24, s24, s39
	v_lshl_add_u64 v[144:145], s[10:11], 0, v[134:135]
	s_mov_b32 m0, s24
	s_nop 0
	global_load_lds_dwordx4 v[144:145], off
	v_lshl_add_u64 v[144:145], s[10:11], 0, v[132:133]
	s_add_i32 m0, s24, 0x2000
	s_nop 0
	global_load_lds_dwordx4 v[144:145], off
	s_waitcnt vmcnt(6)
	s_barrier
	v_mfma_f32_16x16x32_bf16 v[54:57], v[236:239], v[204:207], v[54:57]
	v_mfma_f32_16x16x32_bf16 v[50:53], v[244:247], v[204:207], v[50:53]
	v_mfma_f32_16x16x32_bf16 v[38:41], v[236:239], v[212:215], v[38:41]
	v_mfma_f32_16x16x32_bf16 v[34:37], v[244:247], v[212:215], v[34:37]
	v_mfma_f32_16x16x32_bf16 v[22:25], v[236:239], v[220:223], v[22:25]
	v_mfma_f32_16x16x32_bf16 v[18:21], v[244:247], v[220:223], v[18:21]
	v_mfma_f32_16x16x32_bf16 v[6:9], v[236:239], v[228:231], v[6:9]
	v_mfma_f32_16x16x32_bf16 v[2:5], v[244:247], v[228:231], v[2:5]
	v_mfma_f32_16x16x32_bf16 v[54:57], v[240:243], v[208:211], v[54:57]
	v_mfma_f32_16x16x32_bf16 v[50:53], v[248:251], v[208:211], v[50:53]
	v_mfma_f32_16x16x32_bf16 v[38:41], v[240:243], v[216:219], v[38:41]
	v_mfma_f32_16x16x32_bf16 v[34:37], v[248:251], v[216:219], v[34:37]
	v_mfma_f32_16x16x32_bf16 v[22:25], v[240:243], v[224:227], v[22:25]
	v_mfma_f32_16x16x32_bf16 v[18:21], v[248:251], v[224:227], v[18:21]
	v_mfma_f32_16x16x32_bf16 v[6:9], v[240:243], v[232:235], v[6:9]
	v_mfma_f32_16x16x32_bf16 v[2:5], v[248:251], v[232:235], v[2:5]
	s_add_i32 s30, s30, 2
	s_add_u32 s8, s8, 0x100
	s_addc_u32 s9, s9, 0
	s_add_u32 s28, s28, 0x100
	s_addc_u32 s29, s29, 0
	s_cmp_gt_u32 s30, 13
	s_barrier
	s_cbranch_scc0 .LBB0_335
	s_lshl_b32 s15, s2, 8
	s_add_i32 s15, s15, s44
	v_or_b32_e32 v152, s15, v1
	s_mov_b32 s2, 0xffff
	v_cmp_lt_i32_e64 s[10:11], s2, v152
	s_and_b32 s2, s15, 0xffffff00
	s_add_i32 s2, s2, 0xffff0000
	s_lshl_b64 s[28:29], s[2:3], 10
	s_ashr_i32 s2, s15, 3
	s_and_b32 s8, s2, 0xffffff00
	s_ashr_i32 s9, s8, 31
	s_lshl_b64 s[26:27], s[8:9], 13
	s_lshl_b32 s24, s48, 8
	s_cmp_gt_i32 s48, 6
	s_cselect_b64 s[30:31], -1, 0
	v_bitop3_b32 v146, s15, v186, v1 bitop3:0xc8
	v_bitop3_b32 v148, s15, v187, v1 bitop3:0xc8
	s_mov_b64 s[8:9], -1
	s_and_b64 vcc, exec, s[30:31]
	s_cbranch_vccnz .Lproj_slow_a
;   __device__ __forceinline__ void operator()(const f32x4 (&acc)[2][2][4][2], const Unit& u, int wr, int wc, int fr, int fq) const {
; #pragma unroll
;     for (int ai = 0; ai < 2; ++ai)
; #pragma unroll
;       for (int m = 0; m < 4; ++m) {
;         const int r = u.pm * 256 + ai * 128 + wr * 64 + m * 16 + fr;
; #pragma unroll
;         for (int bj = 0; bj < 2; ++bj)
; #pragma unroll
;           for (int n = 0; n < 2; ++n) {
;             const f32x4 v = acc[ai][bj][m][n];
;             const int c = u.pn * 256 + bj * 128 + wc * 32 + n * 16 + 4 * fq;
;             if (u.pn < 7) {
;               uint2 w; w.x = pack2(v[0], v[1]); w.y = pack2(v[2], v[3]);
;               *reinterpret_cast<uint2*>(PB + (size_t)r * PBW + c) = w;
;     ...
;               const int nn = c - 1792, part = nn >> 8, ch = nn & 255;
;               if (u.pn == 7 && bj == 0 && wc == 1 && n == 1) {
;                 *reinterpret_cast<float4*>(AB + (size_t)r * 16 + 4 * fq) = make_float4(v[0], v[1], v[2], v[3]);
;               } else {
;                 u16* d; int cstride;
;                 if (r < ML) { const int b = r >> 11, tt = r & 2047; d = FT + ((size_t)(b * 256)) * 4096 + part * 2048 + tt; cstride = 4096; }
;                 else { const int rc = r - ML, b = rc >> 8, tt = rc & 255; d = FTC + ((size_t)(b * 256)) * 512 + part * 256 + tt; cstride = 512; }
; #pragma unroll
;                 for (int e = 0; e < 4; ++e) d[(size_t)(ch + e) * cstride] = f2bf(v[e]);
;                 if (u.pn == 7 && bj == 0 && wc == 0) {
; #pragma unroll
;                   for (int e = 0; e < 4; ++e) {
;                     const int kc = n * 16 + 4 * fq + e;
;                     if (kc >= 1 && kc <= 16) d[(size_t)(64 - kc) * cstride] = f2bf(v[e]);
	v_mul_u32_u24_e32 v202, 0xe00, v152
	v_or_b32_e32 v204, s24, v136
	v_lshl_add_u32 v202, v204, 1, v202
	v_bfe_u32 v204, v176, 4, 1
	v_mul_u32_u24_e32 v204, 24, v204
	v_add_u32_e32 v202, v202, v204
	v_cvt_pk_bf16_f32 v208, v126, v127
	v_cvt_pk_bf16_f32 v209, v128, v129
	v_cvt_pk_bf16_f32 v210, v122, v123
	v_cvt_pk_bf16_f32 v211, v124, v125
	v_cvt_pk_bf16_f32 v212, v118, v119
	v_cvt_pk_bf16_f32 v213, v120, v121
	v_cvt_pk_bf16_f32 v214, v114, v115
	v_cvt_pk_bf16_f32 v215, v116, v117
	v_mov_b32_e32 v203, v202
	s_nop 0
	v_permlane16_swap_b32_e32 v208, v210
	v_permlane16_swap_b32_e32 v209, v211
	v_permlane16_swap_b32_e32 v212, v214
	v_permlane16_swap_b32_e32 v213, v215
	global_store_dwordx4 v203, v[208:211], s[84:85]
	global_store_dwordx4 v203, v[212:215], s[84:85] offset:256
	v_cvt_pk_bf16_f32 v216, v110, v111
	v_cvt_pk_bf16_f32 v217, v112, v113
	v_cvt_pk_bf16_f32 v218, v106, v107
	v_cvt_pk_bf16_f32 v219, v108, v109
	v_cvt_pk_bf16_f32 v220, v102, v103
	v_cvt_pk_bf16_f32 v221, v104, v105
	v_cvt_pk_bf16_f32 v222, v98, v99
	v_cvt_pk_bf16_f32 v223, v100, v101
	v_add_u32_e32 v205, 0xe000, v202
	s_nop 0
	v_permlane16_swap_b32_e32 v216, v218
	v_permlane16_swap_b32_e32 v217, v219
	v_permlane16_swap_b32_e32 v220, v222
	v_permlane16_swap_b32_e32 v221, v223
	global_store_dwordx4 v205, v[216:219], s[84:85]
	global_store_dwordx4 v205, v[220:223], s[84:85] offset:256
	v_cvt_pk_bf16_f32 v208, v94, v95
	v_cvt_pk_bf16_f32 v209, v96, v97
	v_cvt_pk_bf16_f32 v210, v90, v91
	v_cvt_pk_bf16_f32 v211, v92, v93
	v_cvt_pk_bf16_f32 v212, v86, v87
	v_cvt_pk_bf16_f32 v213, v88, v89
	v_cvt_pk_bf16_f32 v214, v82, v83
	v_cvt_pk_bf16_f32 v215, v84, v85
	v_add_u32_e32 v206, 0x1c000, v202
	s_nop 0
	v_permlane16_swap_b32_e32 v208, v210
	v_permlane16_swap_b32_e32 v209, v211
	v_permlane16_swap_b32_e32 v212, v214
	v_permlane16_swap_b32_e32 v213, v215
	global_store_dwordx4 v206, v[208:211], s[84:85]
	global_store_dwordx4 v206, v[212:215], s[84:85] offset:256
	v_cvt_pk_bf16_f32 v216, v78, v79
	v_cvt_pk_bf16_f32 v217, v80, v81
	v_cvt_pk_bf16_f32 v218, v74, v75
	v_cvt_pk_bf16_f32 v219, v76, v77
	v_cvt_pk_bf16_f32 v220, v70, v71
	v_cvt_pk_bf16_f32 v221, v72, v73
	v_cvt_pk_bf16_f32 v222, v66, v67
	v_cvt_pk_bf16_f32 v223, v68, v69
	v_add_u32_e32 v205, 0x2a000, v202
	s_nop 0
	v_permlane16_swap_b32_e32 v216, v218
	v_permlane16_swap_b32_e32 v217, v219
	v_permlane16_swap_b32_e32 v220, v222
	v_permlane16_swap_b32_e32 v221, v223
	global_store_dwordx4 v205, v[216:219], s[84:85]
	global_store_dwordx4 v205, v[220:223], s[84:85] offset:256
	v_cvt_pk_bf16_f32 v208, v62, v63
	v_cvt_pk_bf16_f32 v209, v64, v65
	v_cvt_pk_bf16_f32 v210, v58, v59
	v_cvt_pk_bf16_f32 v211, v60, v61
	v_cvt_pk_bf16_f32 v212, v54, v55
	v_cvt_pk_bf16_f32 v213, v56, v57
	v_cvt_pk_bf16_f32 v214, v50, v51
	v_cvt_pk_bf16_f32 v215, v52, v53
	v_add_u32_e32 v206, 0x70000, v202
	s_nop 0
	v_permlane16_swap_b32_e32 v208, v210
	v_permlane16_swap_b32_e32 v209, v211
	v_permlane16_swap_b32_e32 v212, v214
	v_permlane16_swap_b32_e32 v213, v215
	global_store_dwordx4 v206, v[208:211], s[84:85]
	global_store_dwordx4 v206, v[212:215], s[84:85] offset:256
	v_cvt_pk_bf16_f32 v216, v46, v47
	v_cvt_pk_bf16_f32 v217, v48, v49
	v_cvt_pk_bf16_f32 v218, v42, v43
	v_cvt_pk_bf16_f32 v219, v44, v45
	v_cvt_pk_bf16_f32 v220, v38, v39
	v_cvt_pk_bf16_f32 v221, v40, v41
	v_cvt_pk_bf16_f32 v222, v34, v35
	v_cvt_pk_bf16_f32 v223, v36, v37
	v_add_u32_e32 v205, 0x7e000, v202
	s_nop 0
	v_permlane16_swap_b32_e32 v216, v218
	v_permlane16_swap_b32_e32 v217, v219
	v_permlane16_swap_b32_e32 v220, v222
	v_permlane16_swap_b32_e32 v221, v223
	global_store_dwordx4 v205, v[216:219], s[84:85]
	global_store_dwordx4 v205, v[220:223], s[84:85] offset:256
	v_cvt_pk_bf16_f32 v208, v30, v31
	v_cvt_pk_bf16_f32 v209, v32, v33
	v_cvt_pk_bf16_f32 v210, v26, v27
	v_cvt_pk_bf16_f32 v211, v28, v29
	v_cvt_pk_bf16_f32 v212, v22, v23
	v_cvt_pk_bf16_f32 v213, v24, v25
	v_cvt_pk_bf16_f32 v214, v18, v19
	v_cvt_pk_bf16_f32 v215, v20, v21
	v_add_u32_e32 v206, 0x8c000, v202
	s_nop 0
	v_permlane16_swap_b32_e32 v208, v210
	v_permlane16_swap_b32_e32 v209, v211
	v_permlane16_swap_b32_e32 v212, v214
	v_permlane16_swap_b32_e32 v213, v215
	global_store_dwordx4 v206, v[208:211], s[84:85]
	global_store_dwordx4 v206, v[212:215], s[84:85] offset:256
	v_cvt_pk_bf16_f32 v216, v14, v15
	v_cvt_pk_bf16_f32 v217, v16, v17
	v_cvt_pk_bf16_f32 v218, v10, v11
	v_cvt_pk_bf16_f32 v219, v12, v13
	v_cvt_pk_bf16_f32 v220, v6, v7
	v_cvt_pk_bf16_f32 v221, v8, v9
	v_cvt_pk_bf16_f32 v222, v2, v3
	v_cvt_pk_bf16_f32 v223, v4, v5
	v_add_u32_e32 v205, 0x9a000, v202
	s_nop 0
	v_permlane16_swap_b32_e32 v216, v218
	v_permlane16_swap_b32_e32 v217, v219
	v_permlane16_swap_b32_e32 v220, v222
	v_permlane16_swap_b32_e32 v221, v223
	global_store_dwordx4 v205, v[216:219], s[84:85]
	global_store_dwordx4 v205, v[220:223], s[84:85] offset:256
	s_branch .LBB0_328
.Lproj_slow_a:
	s_and_saveexec_b64 s[8:9], s[10:11]
	s_xor_b64 s[8:9], exec, s[8:9]
	s_add_u32 s34, s54, s28
	s_addc_u32 s35, s55, s29
	s_or_saveexec_b64 s[8:9], s[8:9]
	s_add_i32 s2, s24, 0xfffff900
	v_mov_b64_e32 v[144:145], 0x200
	v_mov_b32_e32 v150, s2
	v_mov_b64_e32 v[154:155], s[34:35]
	v_mov_b64_e32 v[156:157], v[146:147]
	s_xor_b64 exec, exec, s[8:9]
	s_add_u32 s34, s69, s26
	s_addc_u32 s35, s52, s27
	s_lshl_b32 s2, s2, 3
	v_mov_b64_e32 v[144:145], 0x1000
	v_mov_b32_e32 v150, s2
	v_mov_b64_e32 v[154:155], s[34:35]
	v_mov_b64_e32 v[156:157], v[148:149]
	s_or_b64 exec, exec, s[8:9]
	v_ashrrev_i32_e32 v151, 31, v150
	v_lshl_add_u64 v[150:151], v[150:151], 1, v[154:155]
	v_lshlrev_b32_e32 v154, 1, v156
	v_mov_b32_e32 v155, v0
	v_mul_u32_u24_e32 v145, v144, v136
	v_lshl_add_u64 v[150:151], v[150:151], 0, v[154:155]
	v_lshlrev_b32_e32 v154, 1, v145
	v_cvt_pk_bf16_f32 v149, v126, s0
	v_lshl_add_u64 v[154:155], v[150:151], 0, v[154:155]
	v_mul_u32_u24_e32 v147, v144, v166
	global_store_short v[154:155], v149, off
	v_lshlrev_b32_e32 v154, 1, v147
	v_mov_b32_e32 v155, v0
	v_cvt_pk_bf16_f32 v145, v127, s0
	v_lshl_add_u64 v[154:155], v[150:151], 0, v[154:155]
	v_mul_u32_u24_e32 v153, v144, v167
	global_store_short v[154:155], v145, off
	v_lshlrev_b32_e32 v154, 1, v153
	v_mov_b32_e32 v155, v0
	s_cmp_lg_u32 s48, 7
	v_cvt_pk_bf16_f32 v147, v128, s0
	v_lshl_add_u64 v[154:155], v[150:151], 0, v[154:155]
	s_cselect_b64 s[8:9], -1, 0
	global_store_short v[154:155], v147, off
	v_mul_u32_u24_e32 v154, v144, v168
	s_xor_b64 s[34:35], s[12:13], -1
	v_lshlrev_b32_e32 v154, 1, v154
	v_mov_b32_e32 v155, v0
	s_or_b64 s[8:9], s[34:35], s[8:9]
	v_cvt_pk_bf16_f32 v153, v129, s0
	v_lshl_add_u64 v[154:155], v[150:151], 0, v[154:155]
	s_and_b64 vcc, exec, s[8:9]
	global_store_short v[154:155], v153, off
	s_cbranch_vccnz .LBB0_345
	s_and_saveexec_b64 s[8:9], s[4:5]
	s_cbranch_execz .LBB0_344
	v_mul_u32_u24_e32 v154, v144, v158
	v_lshlrev_b32_e32 v154, 1, v154
	v_mov_b32_e32 v155, v0
	v_lshl_add_u64 v[154:155], v[150:151], 0, v[154:155]
	global_store_short v[154:155], v149, off

; #define PG8_STAGE(bufoff, gbase, voff) do { _Pragma("unroll") for (int _i = 0; _i < 2; ++_i) \
;     __builtin_amdgcn_global_load_lds((const unsigned*)((const char*)(gbase) + (voff)[_i]), (PG8_LAS unsigned*)(lds + (bufoff) + ldsw + _i * 8192), 16, 0, 0); } while (0)
; #define PG8_LDA(dst, b, h) do { _Pragma("unroll") for (int m = 0; m < 4; ++m) _Pragma("unroll") for (int k = 0; k < 2; ++k) dst[m][k] = *(const PG8_LAS bf16x8*)(lds + PG8_SA(b, h) + aoff + m * 2048 + k * 1024); } while (0)
; #define PG8_LDB(dst, b, h) do { _Pragma("unroll") for (int n = 0; n < 2; ++n) _Pragma("unroll") for (int k = 0; k < 2; ++k) dst[n][k] = *(const PG8_LAS bf16x8*)(lds + PG8_SB(b, h) + boff + n * 2048 + k * 1024); } while (0)
; #define PG8_MMA(ai, bj, At, Bt) do { __builtin_amdgcn_s_setprio(1); _Pragma("unroll") for (int m = 0; m < 4; ++m) _Pragma("unroll") for (int n = 0; n < 2; ++n) _Pragma("unroll") for (int k = 0; k < 2; ++k) \
;     acc[ai][bj][m][n] = __builtin_amdgcn_mfma_f32_16x16x32_bf16(Bt[n][k], At[m][k], acc[ai][bj][m][n], 0, 0, 0); __builtin_amdgcn_s_setprio(0); } while (0)
; #define PG8_WAIT_V(n) asm volatile("s_waitcnt vmcnt(" #n ")" ::: "memory")
; #define PG8_WAIT_L(n) asm volatile("s_waitcnt lgkmcnt(" #n ")" ::: "memory")
; #define PG8_BAR __builtin_amdgcn_s_barrier()
; #define PG8_SCHED __builtin_amdgcn_sched_barrier(0)
; template <class Epi, class Sched>
; __device__ __forceinline__ void gemm_phase(PG8_LAS unsigned char* lds, const int lda, const int ldb, const Sched& S, const Epi& E) {
;     ...
;       PG8_LDB(B0, 0, 0); PG8_SCHED; PG8_LDA(At, 0, 0); PG8_STAGE(PG8_SA(1, 1), a1 + hstepA, voffA);
;       PG8_WAIT_L(8); PG8_BAR; PG8_WAIT_L(0); PG8_MMA(0, 0, At, B0); PG8_BAR; PG8_SCHED;
;       PG8_LDB(B1, 0, 1); PG8_STAGE(PG8_SB(0, 0), b2, voffB);
;       PG8_BAR; PG8_WAIT_L(0); PG8_MMA(0, 1, At, B1); PG8_BAR;
;       PG8_LDA(At, 0, 1); PG8_STAGE(PG8_SA(0, 0), a2, voffA);
;       PG8_BAR; PG8_WAIT_L(0); PG8_MMA(1, 0, At, B0); PG8_BAR; PG8_SCHED;
;       PG8_STAGE(PG8_SB(0, 1), b2 + hstepB, voffB);
;       PG8_WAIT_V(6); PG8_BAR; PG8_MMA(1, 1, At, B1); PG8_BAR;
.LBB0_685:
	s_add_u32 s12, s10, 0xfffc0080
	s_addc_u32 s13, s11, -1
	s_add_i32 s31, 0, 0x10000
	v_add_u32_e32 v156, s31, v131
	ds_read_b128 v[144:147], v156
	ds_read_b128 v[148:151], v156 offset:1024
	ds_read_b128 v[152:155], v156 offset:2048
	ds_read_b128 v[200:203], v156 offset:3072
	s_cmp_eq_u32 s30, 12
	s_cselect_b32 s25, s19, s13
	s_cselect_b32 s24, s26, s12
	s_cselect_b32 s13, s17, s29
	s_cselect_b32 s12, s27, s28
	v_lshl_add_u64 v[156:157], s[10:11], 0, v[140:141]
	s_add_i32 m0, s40, 0xc000
	ds_read_b128 v[204:207], v172
	ds_read_b128 v[208:211], v172 offset:1024
	ds_read_b128 v[212:215], v172 offset:2048
	ds_read_b128 v[216:219], v172 offset:3072
	ds_read_b128 v[220:223], v172 offset:4096
	ds_read_b128 v[224:227], v172 offset:5120
	ds_read_b128 v[228:231], v172 offset:6144
	ds_read_b128 v[232:235], v172 offset:7168
	global_load_lds_dwordx4 v[156:157], off
	v_lshl_add_u64 v[156:157], s[10:11], 0, v[142:143]
	s_add_i32 m0, s40, 0xe000
	s_nop 0
	global_load_lds_dwordx4 v[156:157], off
	s_waitcnt lgkmcnt(8)
	s_barrier
	s_waitcnt lgkmcnt(0)
	v_mfma_f32_16x16x32_bf16 v[126:129], v[144:147], v[204:207], v[126:129]
	v_mfma_f32_16x16x32_bf16 v[122:125], v[152:155], v[204:207], v[122:125]
	v_mfma_f32_16x16x32_bf16 v[110:113], v[144:147], v[212:215], v[110:113]
	v_mfma_f32_16x16x32_bf16 v[106:109], v[152:155], v[212:215], v[106:109]
	v_mfma_f32_16x16x32_bf16 v[94:97], v[144:147], v[220:223], v[94:97]
	v_mfma_f32_16x16x32_bf16 v[90:93], v[152:155], v[220:223], v[90:93]
	v_mfma_f32_16x16x32_bf16 v[78:81], v[144:147], v[228:231], v[78:81]
	v_mfma_f32_16x16x32_bf16 v[74:77], v[152:155], v[228:231], v[74:77]
	v_mfma_f32_16x16x32_bf16 v[126:129], v[148:151], v[208:211], v[126:129]
	v_mfma_f32_16x16x32_bf16 v[122:125], v[200:203], v[208:211], v[122:125]
	v_mfma_f32_16x16x32_bf16 v[110:113], v[148:151], v[216:219], v[110:113]
	v_mfma_f32_16x16x32_bf16 v[106:109], v[200:203], v[216:219], v[106:109]
	v_mfma_f32_16x16x32_bf16 v[94:97], v[148:151], v[224:227], v[94:97]
	v_mfma_f32_16x16x32_bf16 v[90:93], v[200:203], v[224:227], v[90:93]
	v_mfma_f32_16x16x32_bf16 v[78:81], v[148:151], v[232:235], v[78:81]
	v_mfma_f32_16x16x32_bf16 v[74:77], v[200:203], v[232:235], v[74:77]
	s_barrier
	s_add_i32 s33, 0, 0x14000
	v_add_u32_e32 v156, s33, v131
	s_add_i32 s31, s31, s39
	ds_read_b128 v[236:239], v156
	ds_read_b128 v[240:243], v156 offset:1024
	ds_read_b128 v[244:247], v156 offset:2048
	ds_read_b128 v[248:251], v156 offset:3072
	v_lshl_add_u64 v[156:157], s[12:13], 0, v[134:135]
	s_mov_b32 m0, s31
	v_lshl_add_u64 v[174:175], s[12:13], 0, v[132:133]
	global_load_lds_dwordx4 v[156:157], off
	s_add_i32 m0, s31, 0x2000
	s_nop 0
	global_load_lds_dwordx4 v[174:175], off
	s_barrier
	s_waitcnt lgkmcnt(0)
	v_mfma_f32_16x16x32_bf16 v[118:121], v[236:239], v[204:207], v[118:121]
	v_mfma_f32_16x16x32_bf16 v[114:117], v[244:247], v[204:207], v[114:117]
	v_mfma_f32_16x16x32_bf16 v[102:105], v[236:239], v[212:215], v[102:105]
	v_mfma_f32_16x16x32_bf16 v[98:101], v[244:247], v[212:215], v[98:101]
	v_mfma_f32_16x16x32_bf16 v[86:89], v[236:239], v[220:223], v[86:89]
	v_mfma_f32_16x16x32_bf16 v[82:85], v[244:247], v[220:223], v[82:85]
	v_mfma_f32_16x16x32_bf16 v[70:73], v[236:239], v[228:231], v[70:73]
	v_mfma_f32_16x16x32_bf16 v[66:69], v[244:247], v[228:231], v[66:69]
	v_mfma_f32_16x16x32_bf16 v[118:121], v[240:243], v[208:211], v[118:121]
	v_mfma_f32_16x16x32_bf16 v[114:117], v[248:251], v[208:211], v[114:117]
	v_mfma_f32_16x16x32_bf16 v[102:105], v[240:243], v[216:219], v[102:105]
	v_mfma_f32_16x16x32_bf16 v[98:101], v[248:251], v[216:219], v[98:101]
	v_mfma_f32_16x16x32_bf16 v[86:89], v[240:243], v[224:227], v[86:89]
	v_mfma_f32_16x16x32_bf16 v[82:85], v[248:251], v[224:227], v[82:85]
	v_mfma_f32_16x16x32_bf16 v[70:73], v[240:243], v[232:235], v[70:73]
	v_mfma_f32_16x16x32_bf16 v[66:69], v[248:251], v[232:235], v[66:69]
	s_barrier
	s_mov_b32 m0, s40
	v_lshl_add_u64 v[182:183], s[24:25], 0, v[134:135]
	ds_read_b128 v[204:207], v172 offset:16384
	ds_read_b128 v[208:211], v172 offset:17408
	ds_read_b128 v[212:215], v172 offset:18432
	ds_read_b128 v[216:219], v172 offset:19456
	ds_read_b128 v[220:223], v172 offset:20480
	ds_read_b128 v[224:227], v172 offset:21504
	ds_read_b128 v[228:231], v172 offset:22528
	ds_read_b128 v[232:235], v172 offset:23552
	global_load_lds_dwordx4 v[182:183], off
	v_lshl_add_u64 v[184:185], s[24:25], 0, v[132:133]
	s_mov_b32 m0, s41
	s_nop 0
	global_load_lds_dwordx4 v[184:185], off
	s_barrier
	s_waitcnt lgkmcnt(0)
	v_mfma_f32_16x16x32_bf16 v[62:65], v[144:147], v[204:207], v[62:65]
	v_mfma_f32_16x16x32_bf16 v[58:61], v[152:155], v[204:207], v[58:61]
	v_mfma_f32_16x16x32_bf16 v[46:49], v[144:147], v[212:215], v[46:49]
	v_mfma_f32_16x16x32_bf16 v[42:45], v[152:155], v[212:215], v[42:45]
	v_mfma_f32_16x16x32_bf16 v[30:33], v[144:147], v[220:223], v[30:33]
	v_mfma_f32_16x16x32_bf16 v[26:29], v[152:155], v[220:223], v[26:29]
	v_mfma_f32_16x16x32_bf16 v[14:17], v[144:147], v[228:231], v[14:17]
	v_mfma_f32_16x16x32_bf16 v[10:13], v[152:155], v[228:231], v[10:13]
	v_mfma_f32_16x16x32_bf16 v[62:65], v[148:151], v[208:211], v[62:65]
	v_mfma_f32_16x16x32_bf16 v[58:61], v[200:203], v[208:211], v[58:61]
	v_mfma_f32_16x16x32_bf16 v[46:49], v[148:151], v[216:219], v[46:49]
	v_mfma_f32_16x16x32_bf16 v[42:45], v[200:203], v[216:219], v[42:45]
	v_mfma_f32_16x16x32_bf16 v[30:33], v[148:151], v[224:227], v[30:33]
	v_mfma_f32_16x16x32_bf16 v[26:29], v[200:203], v[224:227], v[26:29]
	v_mfma_f32_16x16x32_bf16 v[14:17], v[148:151], v[232:235], v[14:17]
	v_mfma_f32_16x16x32_bf16 v[10:13], v[200:203], v[232:235], v[10:13]
	s_barrier
; #define PG8_STAGE(bufoff, gbase, voff) do { _Pragma("unroll") for (int _i = 0; _i < 2; ++_i) \
;     __builtin_amdgcn_global_load_lds((const unsigned*)((const char*)(gbase) + (voff)[_i]), (PG8_LAS unsigned*)(lds + (bufoff) + ldsw + _i * 8192), 16, 0, 0); } while (0)
; #define PG8_LDA(dst, b, h) do { _Pragma("unroll") for (int m = 0; m < 4; ++m) _Pragma("unroll") for (int k = 0; k < 2; ++k) dst[m][k] = *(const PG8_LAS bf16x8*)(lds + PG8_SA(b, h) + aoff + m * 2048 + k * 1024); } while (0)
; #define PG8_LDB(dst, b, h) do { _Pragma("unroll") for (int n = 0; n < 2; ++n) _Pragma("unroll") for (int k = 0; k < 2; ++k) dst[n][k] = *(const PG8_LAS bf16x8*)(lds + PG8_SB(b, h) + boff + n * 2048 + k * 1024); } while (0)
; #define PG8_MMA(ai, bj, At, Bt) do { __builtin_amdgcn_s_setprio(1); _Pragma("unroll") for (int m = 0; m < 4; ++m) _Pragma("unroll") for (int n = 0; n < 2; ++n) _Pragma("unroll") for (int k = 0; k < 2; ++k) \
;     acc[ai][bj][m][n] = __builtin_amdgcn_mfma_f32_16x16x32_bf16(Bt[n][k], At[m][k], acc[ai][bj][m][n], 0, 0, 0); __builtin_amdgcn_s_setprio(0); } while (0)
; #define PG8_WAIT_V(n) asm volatile("s_waitcnt vmcnt(" #n ")" ::: "memory")
; #define PG8_WAIT_L(n) asm volatile("s_waitcnt lgkmcnt(" #n ")" ::: "memory")
; #define PG8_BAR __builtin_amdgcn_s_barrier()
; #define PG8_SCHED __builtin_amdgcn_sched_barrier(0)
; template <class Epi, class Sched>
; __device__ __forceinline__ void gemm_phase(PG8_LAS unsigned char* lds, const int lda, const int ldb, const Sched& S, const Epi& E) {
;     ...
;       PG8_STAGE(PG8_SB(0, 1), b2 + hstepB, voffB);
;       PG8_WAIT_V(6); PG8_BAR; PG8_MMA(1, 1, At, B1); PG8_BAR;
;       PG8_LDB(B0, 1, 0); PG8_SCHED; PG8_LDA(At, 1, 0); PG8_STAGE(PG8_SA(0, 1), a2 + hstepA, voffA);
;       PG8_WAIT_L(8); PG8_BAR; PG8_WAIT_L(0); PG8_MMA(0, 0, At, B0); PG8_BAR; PG8_SCHED;
;       PG8_LDB(B1, 1, 1); PG8_STAGE(PG8_SB(1, 0), b3, voffB);
;       PG8_BAR; PG8_WAIT_L(0); PG8_MMA(0, 1, At, B1); PG8_BAR;
;       PG8_LDA(At, 1, 1); PG8_STAGE(PG8_SA(1, 0), a3, voffA);
;       PG8_BAR; PG8_WAIT_L(0); PG8_MMA(1, 0, At, B0); PG8_BAR; PG8_SCHED;
	s_add_u32 s34, s12, 0x40000
	s_addc_u32 s35, s13, 0
	s_add_i32 s31, s33, s39
	v_lshl_add_u64 v[144:145], s[34:35], 0, v[134:135]
	s_mov_b32 m0, s31
	s_nop 0
	global_load_lds_dwordx4 v[144:145], off
	v_lshl_add_u64 v[144:145], s[34:35], 0, v[132:133]
	s_add_i32 m0, s31, 0x2000
	s_nop 0
	global_load_lds_dwordx4 v[144:145], off
	s_waitcnt vmcnt(6)
	s_barrier
	v_mfma_f32_16x16x32_bf16 v[54:57], v[236:239], v[204:207], v[54:57]
	v_mfma_f32_16x16x32_bf16 v[50:53], v[244:247], v[204:207], v[50:53]
	v_mfma_f32_16x16x32_bf16 v[38:41], v[236:239], v[212:215], v[38:41]
	v_mfma_f32_16x16x32_bf16 v[34:37], v[244:247], v[212:215], v[34:37]
	v_mfma_f32_16x16x32_bf16 v[22:25], v[236:239], v[220:223], v[22:25]
	v_mfma_f32_16x16x32_bf16 v[18:21], v[244:247], v[220:223], v[18:21]
	v_mfma_f32_16x16x32_bf16 v[6:9], v[236:239], v[228:231], v[6:9]
	v_mfma_f32_16x16x32_bf16 v[2:5], v[244:247], v[228:231], v[2:5]
	v_mfma_f32_16x16x32_bf16 v[54:57], v[240:243], v[208:211], v[54:57]
	v_mfma_f32_16x16x32_bf16 v[50:53], v[248:251], v[208:211], v[50:53]
	v_mfma_f32_16x16x32_bf16 v[38:41], v[240:243], v[216:219], v[38:41]
	v_mfma_f32_16x16x32_bf16 v[34:37], v[248:251], v[216:219], v[34:37]
	v_mfma_f32_16x16x32_bf16 v[22:25], v[240:243], v[224:227], v[22:25]
	v_mfma_f32_16x16x32_bf16 v[18:21], v[248:251], v[224:227], v[18:21]
	v_mfma_f32_16x16x32_bf16 v[6:9], v[240:243], v[232:235], v[6:9]
	v_mfma_f32_16x16x32_bf16 v[2:5], v[248:251], v[232:235], v[2:5]
	s_barrier
	s_add_i32 s31, 0, 0x18000
	v_add_u32_e32 v173, s31, v131
	ds_read_b128 v[144:147], v173
	ds_read_b128 v[148:151], v173 offset:1024
	ds_read_b128 v[152:155], v173 offset:2048
	ds_read_b128 v[200:203], v173 offset:3072
	s_add_u32 s24, s24, 0x40000
	s_addc_u32 s25, s25, 0
	s_mov_b32 m0, s42
	v_lshl_add_u64 v[236:237], s[24:25], 0, v[134:135]
	ds_read_b128 v[204:207], v172 offset:32768
	ds_read_b128 v[208:211], v172 offset:33792
	ds_read_b128 v[212:215], v172 offset:34816
	ds_read_b128 v[216:219], v172 offset:35840
	ds_read_b128 v[220:223], v172 offset:36864
	ds_read_b128 v[224:227], v172 offset:37888
	ds_read_b128 v[228:231], v172 offset:38912
	ds_read_b128 v[232:235], v172 offset:39936
	global_load_lds_dwordx4 v[236:237], off
	v_lshl_add_u64 v[236:237], s[24:25], 0, v[132:133]
	s_mov_b32 m0, s43
	s_nop 0
	global_load_lds_dwordx4 v[236:237], off
	s_waitcnt lgkmcnt(8)
	s_barrier
	s_waitcnt lgkmcnt(0)
	v_mfma_f32_16x16x32_bf16 v[126:129], v[144:147], v[204:207], v[126:129]
	v_mfma_f32_16x16x32_bf16 v[122:125], v[152:155], v[204:207], v[122:125]
	v_mfma_f32_16x16x32_bf16 v[110:113], v[144:147], v[212:215], v[110:113]
	v_mfma_f32_16x16x32_bf16 v[106:109], v[152:155], v[212:215], v[106:109]
	v_mfma_f32_16x16x32_bf16 v[94:97], v[144:147], v[220:223], v[94:97]
	v_mfma_f32_16x16x32_bf16 v[90:93], v[152:155], v[220:223], v[90:93]
	v_mfma_f32_16x16x32_bf16 v[78:81], v[144:147], v[228:231], v[78:81]
	v_mfma_f32_16x16x32_bf16 v[74:77], v[152:155], v[228:231], v[74:77]
	v_mfma_f32_16x16x32_bf16 v[126:129], v[148:151], v[208:211], v[126:129]
	v_mfma_f32_16x16x32_bf16 v[122:125], v[200:203], v[208:211], v[122:125]
	v_mfma_f32_16x16x32_bf16 v[110:113], v[148:151], v[216:219], v[110:113]
	v_mfma_f32_16x16x32_bf16 v[106:109], v[200:203], v[216:219], v[106:109]
	v_mfma_f32_16x16x32_bf16 v[94:97], v[148:151], v[224:227], v[94:97]
	v_mfma_f32_16x16x32_bf16 v[90:93], v[200:203], v[224:227], v[90:93]
	v_mfma_f32_16x16x32_bf16 v[78:81], v[148:151], v[232:235], v[78:81]
	v_mfma_f32_16x16x32_bf16 v[74:77], v[200:203], v[232:235], v[74:77]
	s_barrier
	s_add_i32 s24, 0, 0x1c000
	s_add_i32 s25, s31, s39
	v_add_u32_e32 v173, s24, v131
	v_lshl_add_u64 v[156:157], v[156:157], 0, s[86:87]
	s_mov_b32 m0, s25
	ds_read_b128 v[236:239], v173
	ds_read_b128 v[240:243], v173 offset:1024
	ds_read_b128 v[244:247], v173 offset:2048
	ds_read_b128 v[248:251], v173 offset:3072
	global_load_lds_dwordx4 v[156:157], off
	v_lshl_add_u64 v[156:157], v[174:175], 0, s[86:87]
	s_add_i32 m0, s25, 0x2000
	s_nop 0
	global_load_lds_dwordx4 v[156:157], off
	s_barrier
	s_waitcnt lgkmcnt(0)
	v_mfma_f32_16x16x32_bf16 v[118:121], v[236:239], v[204:207], v[118:121]
	v_mfma_f32_16x16x32_bf16 v[114:117], v[244:247], v[204:207], v[114:117]
	v_mfma_f32_16x16x32_bf16 v[102:105], v[236:239], v[212:215], v[102:105]
	v_mfma_f32_16x16x32_bf16 v[98:101], v[244:247], v[212:215], v[98:101]
	v_mfma_f32_16x16x32_bf16 v[86:89], v[236:239], v[220:223], v[86:89]
	v_mfma_f32_16x16x32_bf16 v[82:85], v[244:247], v[220:223], v[82:85]
	v_mfma_f32_16x16x32_bf16 v[70:73], v[236:239], v[228:231], v[70:73]
	v_mfma_f32_16x16x32_bf16 v[66:69], v[244:247], v[228:231], v[66:69]
	v_mfma_f32_16x16x32_bf16 v[118:121], v[240:243], v[208:211], v[118:121]
	v_mfma_f32_16x16x32_bf16 v[114:117], v[248:251], v[208:211], v[114:117]
	v_mfma_f32_16x16x32_bf16 v[102:105], v[240:243], v[216:219], v[102:105]
	v_mfma_f32_16x16x32_bf16 v[98:101], v[248:251], v[216:219], v[98:101]
	v_mfma_f32_16x16x32_bf16 v[86:89], v[240:243], v[224:227], v[86:89]
	v_mfma_f32_16x16x32_bf16 v[82:85], v[248:251], v[224:227], v[82:85]
	v_mfma_f32_16x16x32_bf16 v[70:73], v[240:243], v[232:235], v[70:73]
	v_mfma_f32_16x16x32_bf16 v[66:69], v[248:251], v[232:235], v[66:69]
	s_barrier
	s_mov_b32 m0, s45
	v_lshl_add_u64 v[156:157], v[182:183], 0, s[86:87]
	ds_read_b128 v[204:207], v172 offset:49152
	ds_read_b128 v[208:211], v172 offset:50176
	ds_read_b128 v[212:215], v172 offset:51200
	ds_read_b128 v[216:219], v172 offset:52224
	ds_read_b128 v[220:223], v172 offset:53248
	ds_read_b128 v[224:227], v172 offset:54272
	ds_read_b128 v[228:231], v172 offset:55296
	ds_read_b128 v[232:235], v172 offset:56320
	global_load_lds_dwordx4 v[156:157], off
	v_lshl_add_u64 v[156:157], v[184:185], 0, s[86:87]
	s_mov_b32 m0, s46
	s_nop 0
	global_load_lds_dwordx4 v[156:157], off
	s_barrier
; #define PG8_STAGE(bufoff, gbase, voff) do { _Pragma("unroll") for (int _i = 0; _i < 2; ++_i) \
;     __builtin_amdgcn_global_load_lds((const unsigned*)((const char*)(gbase) + (voff)[_i]), (PG8_LAS unsigned*)(lds + (bufoff) + ldsw + _i * 8192), 16, 0, 0); } while (0)
; #define PG8_MMA(ai, bj, At, Bt) do { __builtin_amdgcn_s_setprio(1); _Pragma("unroll") for (int m = 0; m < 4; ++m) _Pragma("unroll") for (int n = 0; n < 2; ++n) _Pragma("unroll") for (int k = 0; k < 2; ++k) \
;     acc[ai][bj][m][n] = __builtin_amdgcn_mfma_f32_16x16x32_bf16(Bt[n][k], At[m][k], acc[ai][bj][m][n], 0, 0, 0); __builtin_amdgcn_s_setprio(0); } while (0)
; template <class Epi, class Sched>
; __device__ __forceinline__ void gemm_phase(PG8_LAS unsigned char* lds, const int lda, const int ldb, const Sched& S, const Epi& E) {
;     ...
;       PG8_BAR; PG8_WAIT_L(0); PG8_MMA(1, 0, At, B0); PG8_BAR; PG8_SCHED;
;       PG8_STAGE(PG8_SB(1, 1), b3 + hstepB, voffB);
;       PG8_WAIT_V(6); PG8_BAR; PG8_MMA(1, 1, At, B1); PG8_BAR;
;   __device__ __forceinline__ void operator()(const f32x4 (&acc)[2][2][4][2], const Unit& u, int wr, int wc, int fr, int fq) const {
; #pragma unroll
;     for (int ai = 0; ai < 2; ++ai)
; #pragma unroll
;       for (int m = 0; m < 4; ++m) {
;         const int r = u.pm * 256 + ai * 128 + wr * 64 + m * 16 + fr;
; #pragma unroll
;         for (int bj = 0; bj < 2; ++bj)
; #pragma unroll
;           for (int n = 0; n < 2; ++n) {
;             const f32x4 v = acc[ai][bj][m][n];
;             const int c = u.pn * 256 + bj * 128 + wc * 32 + n * 16 + 4 * fq;
;             if (u.pn < 7) {
;               uint2 w; w.x = pack2(v[0], v[1]); w.y = pack2(v[2], v[3]);
;               *reinterpret_cast<uint2*>(PB + (size_t)r * PBW + c) = w;
;             } else {
;               const int nn = c - 1792, part = nn >> 8, ch = nn & 255;
;               if (u.pn == 7 && bj == 0 && wc == 1 && n == 1) {
;                 *reinterpret_cast<float4*>(AB + (size_t)r * 16 + 4 * fq) = make_float4(v[0], v[1], v[2], v[3]);
;               } else {
;                 u16* d; int cstride;
;                 if (r < ML) { const int b = r >> 11, tt = r & 2047; d = FT + ((size_t)(b * 256)) * 4096 + part * 2048 + tt; cstride = 4096; }
;                 else { const int rc = r - ML, b = rc >> 8, tt = rc & 255; d = FTC + ((size_t)(b * 256)) * 512 + part * 256 + tt; cstride = 512; }
	s_waitcnt lgkmcnt(0)
	v_mfma_f32_16x16x32_bf16 v[62:65], v[144:147], v[204:207], v[62:65]
	v_mfma_f32_16x16x32_bf16 v[58:61], v[152:155], v[204:207], v[58:61]
	v_mfma_f32_16x16x32_bf16 v[46:49], v[144:147], v[212:215], v[46:49]
	v_mfma_f32_16x16x32_bf16 v[42:45], v[152:155], v[212:215], v[42:45]
	v_mfma_f32_16x16x32_bf16 v[30:33], v[144:147], v[220:223], v[30:33]
	v_mfma_f32_16x16x32_bf16 v[26:29], v[152:155], v[220:223], v[26:29]
	v_mfma_f32_16x16x32_bf16 v[14:17], v[144:147], v[228:231], v[14:17]
	v_mfma_f32_16x16x32_bf16 v[10:13], v[152:155], v[228:231], v[10:13]
	v_mfma_f32_16x16x32_bf16 v[62:65], v[148:151], v[208:211], v[62:65]
	v_mfma_f32_16x16x32_bf16 v[58:61], v[200:203], v[208:211], v[58:61]
	v_mfma_f32_16x16x32_bf16 v[46:49], v[148:151], v[216:219], v[46:49]
	v_mfma_f32_16x16x32_bf16 v[42:45], v[200:203], v[216:219], v[42:45]
	v_mfma_f32_16x16x32_bf16 v[30:33], v[148:151], v[224:227], v[30:33]
	v_mfma_f32_16x16x32_bf16 v[26:29], v[200:203], v[224:227], v[26:29]
	v_mfma_f32_16x16x32_bf16 v[14:17], v[148:151], v[232:235], v[14:17]
	v_mfma_f32_16x16x32_bf16 v[10:13], v[200:203], v[232:235], v[10:13]
	s_barrier
	s_add_u32 s12, s12, 0x40080
	s_addc_u32 s13, s13, 0
	s_add_i32 s24, s24, s39
	v_lshl_add_u64 v[144:145], s[12:13], 0, v[134:135]
	s_mov_b32 m0, s24
	s_nop 0
	global_load_lds_dwordx4 v[144:145], off
	v_lshl_add_u64 v[144:145], s[12:13], 0, v[132:133]
	s_add_i32 m0, s24, 0x2000
	s_nop 0
	global_load_lds_dwordx4 v[144:145], off
	s_waitcnt vmcnt(6)
	s_barrier
	v_mfma_f32_16x16x32_bf16 v[54:57], v[236:239], v[204:207], v[54:57]
	v_mfma_f32_16x16x32_bf16 v[50:53], v[244:247], v[204:207], v[50:53]
	v_mfma_f32_16x16x32_bf16 v[38:41], v[236:239], v[212:215], v[38:41]
	v_mfma_f32_16x16x32_bf16 v[34:37], v[244:247], v[212:215], v[34:37]
	v_mfma_f32_16x16x32_bf16 v[22:25], v[236:239], v[220:223], v[22:25]
	v_mfma_f32_16x16x32_bf16 v[18:21], v[244:247], v[220:223], v[18:21]
	v_mfma_f32_16x16x32_bf16 v[6:9], v[236:239], v[228:231], v[6:9]
	v_mfma_f32_16x16x32_bf16 v[2:5], v[244:247], v[228:231], v[2:5]
	v_mfma_f32_16x16x32_bf16 v[54:57], v[240:243], v[208:211], v[54:57]
	v_mfma_f32_16x16x32_bf16 v[50:53], v[248:251], v[208:211], v[50:53]
	v_mfma_f32_16x16x32_bf16 v[38:41], v[240:243], v[216:219], v[38:41]
	v_mfma_f32_16x16x32_bf16 v[34:37], v[248:251], v[216:219], v[34:37]
	v_mfma_f32_16x16x32_bf16 v[22:25], v[240:243], v[224:227], v[22:25]
	v_mfma_f32_16x16x32_bf16 v[18:21], v[248:251], v[224:227], v[18:21]
	v_mfma_f32_16x16x32_bf16 v[6:9], v[240:243], v[232:235], v[6:9]
	v_mfma_f32_16x16x32_bf16 v[2:5], v[248:251], v[232:235], v[2:5]
	s_add_i32 s30, s30, 2
	s_add_u32 s10, s10, 0x100
	s_addc_u32 s11, s11, 0
	s_add_u32 s28, s28, 0x100
	s_addc_u32 s29, s29, 0
	s_cmp_gt_u32 s30, 13
	s_barrier
	s_cbranch_scc0 .LBB0_685
	s_lshl_b32 s17, s2, 8
	s_add_i32 s17, s17, s44
	v_or_b32_e32 v152, s17, v1
	s_mov_b32 s2, 0xffff
	v_cmp_lt_i32_e64 s[12:13], s2, v152
	s_and_b32 s2, s17, 0xffffff00
	s_add_i32 s2, s2, 0xffff0000
	s_lshl_b64 s[28:29], s[2:3], 10
	s_ashr_i32 s2, s17, 3
	s_and_b32 s10, s2, 0xffffff00
	s_ashr_i32 s11, s10, 31
	s_lshl_b64 s[26:27], s[10:11], 13
	s_lshl_b32 s24, s48, 8
	s_cmp_gt_i32 s48, 6
	s_cselect_b64 s[30:31], -1, 0
	v_bitop3_b32 v146, s17, v186, v1 bitop3:0xc8
	v_bitop3_b32 v148, s17, v187, v1 bitop3:0xc8
	s_mov_b64 s[10:11], -1
	s_and_b64 vcc, exec, s[30:31]
	s_cbranch_vccnz .Lproj_slow_b
;   __device__ __forceinline__ void operator()(const f32x4 (&acc)[2][2][4][2], const Unit& u, int wr, int wc, int fr, int fq) const {
; #pragma unroll
;     for (int ai = 0; ai < 2; ++ai)
; #pragma unroll
;       for (int m = 0; m < 4; ++m) {
;         const int r = u.pm * 256 + ai * 128 + wr * 64 + m * 16 + fr;
; #pragma unroll
;         for (int bj = 0; bj < 2; ++bj)
; #pragma unroll
;           for (int n = 0; n < 2; ++n) {
;             const f32x4 v = acc[ai][bj][m][n];
;             const int c = u.pn * 256 + bj * 128 + wc * 32 + n * 16 + 4 * fq;
;             if (u.pn < 7) {
;               uint2 w; w.x = pack2(v[0], v[1]); w.y = pack2(v[2], v[3]);
;               *reinterpret_cast<uint2*>(PB + (size_t)r * PBW + c) = w;
;     ...
;               const int nn = c - 1792, part = nn >> 8, ch = nn & 255;
;               if (u.pn == 7 && bj == 0 && wc == 1 && n == 1) {
;                 *reinterpret_cast<float4*>(AB + (size_t)r * 16 + 4 * fq) = make_float4(v[0], v[1], v[2], v[3]);
;               } else {
;                 u16* d; int cstride;
;                 if (r < ML) { const int b = r >> 11, tt = r & 2047; d = FT + ((size_t)(b * 256)) * 4096 + part * 2048 + tt; cstride = 4096; }
;                 else { const int rc = r - ML, b = rc >> 8, tt = rc & 255; d = FTC + ((size_t)(b * 256)) * 512 + part * 256 + tt; cstride = 512; }
; #pragma unroll
;                 for (int e = 0; e < 4; ++e) d[(size_t)(ch + e) * cstride] = f2bf(v[e]);
;                 if (u.pn == 7 && bj == 0 && wc == 0) {
; #pragma unroll
;                   for (int e = 0; e < 4; ++e) {
;                     const int kc = n * 16 + 4 * fq + e;
;                     if (kc >= 1 && kc <= 16) d[(size_t)(64 - kc) * cstride] = f2bf(v[e]);
	v_mul_u32_u24_e32 v202, 0xe00, v152
	v_or_b32_e32 v204, s24, v136
	v_lshl_add_u32 v202, v204, 1, v202
	v_bfe_u32 v204, v176, 4, 1
	v_mul_u32_u24_e32 v204, 24, v204
	v_add_u32_e32 v202, v202, v204
	v_cvt_pk_bf16_f32 v208, v126, v127
	v_cvt_pk_bf16_f32 v209, v128, v129
	v_cvt_pk_bf16_f32 v210, v122, v123
	v_cvt_pk_bf16_f32 v211, v124, v125
	v_cvt_pk_bf16_f32 v212, v118, v119
	v_cvt_pk_bf16_f32 v213, v120, v121
	v_cvt_pk_bf16_f32 v214, v114, v115
	v_cvt_pk_bf16_f32 v215, v116, v117
	v_mov_b32_e32 v203, v202
	s_nop 0
	v_permlane16_swap_b32_e32 v208, v210
	v_permlane16_swap_b32_e32 v209, v211
	v_permlane16_swap_b32_e32 v212, v214
	v_permlane16_swap_b32_e32 v213, v215
	global_store_dwordx4 v203, v[208:211], s[84:85]
	global_store_dwordx4 v203, v[212:215], s[84:85] offset:256
	v_cvt_pk_bf16_f32 v216, v110, v111
	v_cvt_pk_bf16_f32 v217, v112, v113
	v_cvt_pk_bf16_f32 v218, v106, v107
	v_cvt_pk_bf16_f32 v219, v108, v109
	v_cvt_pk_bf16_f32 v220, v102, v103
	v_cvt_pk_bf16_f32 v221, v104, v105
	v_cvt_pk_bf16_f32 v222, v98, v99
	v_cvt_pk_bf16_f32 v223, v100, v101
	v_add_u32_e32 v205, 0xe000, v202
	s_nop 0
	v_permlane16_swap_b32_e32 v216, v218
	v_permlane16_swap_b32_e32 v217, v219
	v_permlane16_swap_b32_e32 v220, v222
	v_permlane16_swap_b32_e32 v221, v223
	global_store_dwordx4 v205, v[216:219], s[84:85]
	global_store_dwordx4 v205, v[220:223], s[84:85] offset:256
	v_cvt_pk_bf16_f32 v208, v94, v95
	v_cvt_pk_bf16_f32 v209, v96, v97
	v_cvt_pk_bf16_f32 v210, v90, v91
	v_cvt_pk_bf16_f32 v211, v92, v93
	v_cvt_pk_bf16_f32 v212, v86, v87
	v_cvt_pk_bf16_f32 v213, v88, v89
	v_cvt_pk_bf16_f32 v214, v82, v83
	v_cvt_pk_bf16_f32 v215, v84, v85
	v_add_u32_e32 v206, 0x1c000, v202
	s_nop 0
	v_permlane16_swap_b32_e32 v208, v210
	v_permlane16_swap_b32_e32 v209, v211
	v_permlane16_swap_b32_e32 v212, v214
	v_permlane16_swap_b32_e32 v213, v215
	global_store_dwordx4 v206, v[208:211], s[84:85]
	global_store_dwordx4 v206, v[212:215], s[84:85] offset:256
	v_cvt_pk_bf16_f32 v216, v78, v79
	v_cvt_pk_bf16_f32 v217, v80, v81
	v_cvt_pk_bf16_f32 v218, v74, v75
	v_cvt_pk_bf16_f32 v219, v76, v77
	v_cvt_pk_bf16_f32 v220, v70, v71
	v_cvt_pk_bf16_f32 v221, v72, v73
	v_cvt_pk_bf16_f32 v222, v66, v67
	v_cvt_pk_bf16_f32 v223, v68, v69
	v_add_u32_e32 v205, 0x2a000, v202
	s_nop 0
	v_permlane16_swap_b32_e32 v216, v218
	v_permlane16_swap_b32_e32 v217, v219
	v_permlane16_swap_b32_e32 v220, v222
	v_permlane16_swap_b32_e32 v221, v223
	global_store_dwordx4 v205, v[216:219], s[84:85]
	global_store_dwordx4 v205, v[220:223], s[84:85] offset:256
	v_cvt_pk_bf16_f32 v208, v62, v63
	v_cvt_pk_bf16_f32 v209, v64, v65
	v_cvt_pk_bf16_f32 v210, v58, v59
	v_cvt_pk_bf16_f32 v211, v60, v61
	v_cvt_pk_bf16_f32 v212, v54, v55
	v_cvt_pk_bf16_f32 v213, v56, v57
	v_cvt_pk_bf16_f32 v214, v50, v51
	v_cvt_pk_bf16_f32 v215, v52, v53
	v_add_u32_e32 v206, 0x70000, v202
	s_nop 0
	v_permlane16_swap_b32_e32 v208, v210
	v_permlane16_swap_b32_e32 v209, v211
	v_permlane16_swap_b32_e32 v212, v214
	v_permlane16_swap_b32_e32 v213, v215
	global_store_dwordx4 v206, v[208:211], s[84:85]
	global_store_dwordx4 v206, v[212:215], s[84:85] offset:256
	v_cvt_pk_bf16_f32 v216, v46, v47
	v_cvt_pk_bf16_f32 v217, v48, v49
	v_cvt_pk_bf16_f32 v218, v42, v43
	v_cvt_pk_bf16_f32 v219, v44, v45
	v_cvt_pk_bf16_f32 v220, v38, v39
	v_cvt_pk_bf16_f32 v221, v40, v41
	v_cvt_pk_bf16_f32 v222, v34, v35
	v_cvt_pk_bf16_f32 v223, v36, v37
	v_add_u32_e32 v205, 0x7e000, v202
	s_nop 0
	v_permlane16_swap_b32_e32 v216, v218
	v_permlane16_swap_b32_e32 v217, v219
	v_permlane16_swap_b32_e32 v220, v222
	v_permlane16_swap_b32_e32 v221, v223
	global_store_dwordx4 v205, v[216:219], s[84:85]
	global_store_dwordx4 v205, v[220:223], s[84:85] offset:256
	v_cvt_pk_bf16_f32 v208, v30, v31
	v_cvt_pk_bf16_f32 v209, v32, v33
	v_cvt_pk_bf16_f32 v210, v26, v27
	v_cvt_pk_bf16_f32 v211, v28, v29
	v_cvt_pk_bf16_f32 v212, v22, v23
	v_cvt_pk_bf16_f32 v213, v24, v25
	v_cvt_pk_bf16_f32 v214, v18, v19
	v_cvt_pk_bf16_f32 v215, v20, v21
	v_add_u32_e32 v206, 0x8c000, v202
	s_nop 0
	v_permlane16_swap_b32_e32 v208, v210
	v_permlane16_swap_b32_e32 v209, v211
	v_permlane16_swap_b32_e32 v212, v214
	v_permlane16_swap_b32_e32 v213, v215
	global_store_dwordx4 v206, v[208:211], s[84:85]
	global_store_dwordx4 v206, v[212:215], s[84:85] offset:256
	v_cvt_pk_bf16_f32 v216, v14, v15
	v_cvt_pk_bf16_f32 v217, v16, v17
	v_cvt_pk_bf16_f32 v218, v10, v11
	v_cvt_pk_bf16_f32 v219, v12, v13
	v_cvt_pk_bf16_f32 v220, v6, v7
	v_cvt_pk_bf16_f32 v221, v8, v9
	v_cvt_pk_bf16_f32 v222, v2, v3
	v_cvt_pk_bf16_f32 v223, v4, v5
	v_add_u32_e32 v205, 0x9a000, v202
	s_nop 0
	v_permlane16_swap_b32_e32 v216, v218
	v_permlane16_swap_b32_e32 v217, v219
	v_permlane16_swap_b32_e32 v220, v222
	v_permlane16_swap_b32_e32 v221, v223
	global_store_dwordx4 v205, v[216:219], s[84:85]
	global_store_dwordx4 v205, v[220:223], s[84:85] offset:256
	s_branch .LBB0_681
.Lproj_slow_b:
	s_and_saveexec_b64 s[10:11], s[12:13]
	s_xor_b64 s[10:11], exec, s[10:11]
	s_add_u32 s34, s54, s28
	s_addc_u32 s35, s55, s29
	s_or_saveexec_b64 s[10:11], s[10:11]
	s_add_i32 s2, s24, 0xfffff900
	v_mov_b64_e32 v[144:145], 0x200
	v_mov_b32_e32 v150, s2
	v_mov_b64_e32 v[154:155], s[34:35]
	v_mov_b64_e32 v[156:157], v[146:147]
	s_xor_b64 exec, exec, s[10:11]
	s_add_u32 s34, s69, s26
	s_addc_u32 s35, s52, s27
	s_lshl_b32 s2, s2, 3
	v_mov_b64_e32 v[144:145], 0x1000
	v_mov_b32_e32 v150, s2
	v_mov_b64_e32 v[154:155], s[34:35]
	v_mov_b64_e32 v[156:157], v[148:149]
	s_or_b64 exec, exec, s[10:11]
	v_ashrrev_i32_e32 v151, 31, v150
	v_lshl_add_u64 v[150:151], v[150:151], 1, v[154:155]
	v_lshlrev_b32_e32 v154, 1, v156
	v_mov_b32_e32 v155, v0
	v_mul_u32_u24_e32 v145, v144, v136
	v_lshl_add_u64 v[150:151], v[150:151], 0, v[154:155]
	v_lshlrev_b32_e32 v154, 1, v145
	v_cvt_pk_bf16_f32 v149, v126, s0
	v_lshl_add_u64 v[154:155], v[150:151], 0, v[154:155]
	v_mul_u32_u24_e32 v147, v144, v166
	global_store_short v[154:155], v149, off
	v_lshlrev_b32_e32 v154, 1, v147
	v_mov_b32_e32 v155, v0
	v_cvt_pk_bf16_f32 v145, v127, s0
	v_lshl_add_u64 v[154:155], v[150:151], 0, v[154:155]
	v_mul_u32_u24_e32 v153, v144, v167
	global_store_short v[154:155], v145, off
	v_lshlrev_b32_e32 v154, 1, v153
	v_mov_b32_e32 v155, v0
	s_cmp_lg_u32 s48, 7
	v_cvt_pk_bf16_f32 v147, v128, s0
	v_lshl_add_u64 v[154:155], v[150:151], 0, v[154:155]
	s_cselect_b64 s[10:11], -1, 0
	global_store_short v[154:155], v147, off
	v_mul_u32_u24_e32 v154, v144, v168
	s_xor_b64 s[34:35], s[14:15], -1
	v_lshlrev_b32_e32 v154, 1, v154
	v_mov_b32_e32 v155, v0
	s_or_b64 s[10:11], s[34:35], s[10:11]
	v_cvt_pk_bf16_f32 v153, v129, s0
	v_lshl_add_u64 v[154:155], v[150:151], 0, v[154:155]
	s_and_b64 vcc, exec, s[10:11]
	global_store_short v[154:155], v153, off
	s_cbranch_vccnz .LBB0_695
	s_and_saveexec_b64 s[10:11], s[4:5]
	s_cbranch_execz .LBB0_694
	v_mul_u32_u24_e32 v154, v144, v158
	v_lshlrev_b32_e32 v154, 1, v154
	v_mov_b32_e32 v155, v0
	v_lshl_add_u64 v[154:155], v[150:151], 0, v[154:155]
	global_store_short v[154:155], v149, off
